# baseline (speedup 1.0000x reference)
.LBB0_413:
	v_add_u32_e32 v242, s27, v234
	ds_read_b64_tr_b16 v[160:161], v242 offset:0x0
	ds_read_b64_tr_b16 v[162:163], v242 offset:0x100
	ds_read_b64_tr_b16 v[164:165], v242 offset:0x1000
	ds_read_b64_tr_b16 v[166:167], v242 offset:0x1100
	s_waitcnt lgkmcnt(2)
	v_mfma_f32_32x32x16_bf16 v[128:143], v[216:219], v[160:163], v[128:143]
	ds_read_b64_tr_b16 v[168:169], v242 offset:0x200
	s_nop 0
	v_mfma_f32_32x32x16_bf16 v[96:111], v[212:215], v[160:163], v[96:111]
	ds_read_b64_tr_b16 v[170:171], v242 offset:0x300
	s_waitcnt lgkmcnt(2)
	v_mfma_f32_32x32x16_bf16 v[128:143], v[224:227], v[164:167], v[128:143]
	ds_read_b64_tr_b16 v[172:173], v242 offset:0x1200
	s_nop 0
	v_mfma_f32_32x32x16_bf16 v[96:111], v[220:223], v[164:167], v[96:111]
	ds_read_b64_tr_b16 v[174:175], v242 offset:0x1300
	s_waitcnt lgkmcnt(2)
	v_mfma_f32_32x32x16_bf16 v[112:127], v[216:219], v[168:171], v[112:127]
	ds_read_b64_tr_b16 v[160:161], v242 offset:0x400
	s_nop 0
	v_mfma_f32_32x32x16_bf16 v[80:95], v[212:215], v[168:171], v[80:95]
	ds_read_b64_tr_b16 v[162:163], v242 offset:0x500
	s_waitcnt lgkmcnt(2)
	v_mfma_f32_32x32x16_bf16 v[112:127], v[224:227], v[172:175], v[112:127]
	ds_read_b64_tr_b16 v[164:165], v242 offset:0x1400
	s_nop 0
	v_mfma_f32_32x32x16_bf16 v[80:95], v[220:223], v[172:175], v[80:95]
	ds_read_b64_tr_b16 v[166:167], v242 offset:0x1500
	ds_read_b128 v[144:147], v241 offset:0x2000
	ds_read_b128 v[148:151], v240 offset:0x2000
	ds_read_b128 v[152:155], v239 offset:0x2000
	ds_read_b128 v[156:159], v0 offset:0x2000
	s_waitcnt lgkmcnt(6)
	v_mfma_f32_32x32x16_bf16 v[64:79], v[216:219], v[160:163], v[64:79]
	ds_read_b64_tr_b16 v[168:169], v242 offset:0x600
	s_nop 0
	v_mfma_f32_32x32x16_bf16 v[32:47], v[212:215], v[160:163], v[32:47]
	ds_read_b64_tr_b16 v[170:171], v242 offset:0x700
	s_waitcnt lgkmcnt(6)
	v_mfma_f32_32x32x16_bf16 v[64:79], v[224:227], v[164:167], v[64:79]
	ds_read_b64_tr_b16 v[172:173], v242 offset:0x1600
	s_nop 0
	v_mfma_f32_32x32x16_bf16 v[32:47], v[220:223], v[164:167], v[32:47]
	ds_read_b64_tr_b16 v[174:175], v242 offset:0x1700
	s_waitcnt lgkmcnt(2)
	v_mfma_f32_32x32x16_bf16 v[48:63], v[216:219], v[168:171], v[48:63]
	s_nop 0
	v_mfma_f32_32x32x16_bf16 v[16:31], v[212:215], v[168:171], v[16:31]
	s_waitcnt lgkmcnt(0)
	v_mfma_f32_32x32x16_bf16 v[48:63], v[224:227], v[172:175], v[48:63]
	s_nop 0
	v_mfma_f32_32x32x16_bf16 v[16:31], v[220:223], v[172:175], v[16:31]
	s_waitcnt lgkmcnt(0)
	v_mfma_f32_32x32x16_bf16 v[212:227], v[144:147], v[176:179], 0
	v_mfma_f32_32x32x16_bf16 v[212:227], v[148:151], v[180:183], v[212:227]
	v_mfma_f32_32x32x16_bf16 v[212:227], v[152:155], v[184:187], v[212:227]
	v_mfma_f32_32x32x16_bf16 v[212:227], v[156:159], v[188:191], v[212:227]
	ds_read_b128 v[144:147], v241 offset:0x2080
	ds_read_b128 v[148:151], v240 offset:0x2080
	ds_read_b128 v[152:155], v239 offset:0x2080
	ds_read_b128 v[156:159], v0 offset:0x2080
	v_cmp_eq_f32_e32 vcc, 0, v238
	v_cmp_eq_f32_e64 s[10:11], 0, v237
	s_and_b64 s[0:1], vcc, s[10:11]
	s_cmp_eq_u64 s[0:1], exec
	s_waitcnt lgkmcnt(0)
	v_mfma_f32_32x32x16_bf16 v[160:175], v[144:147], v[192:195], 0
	v_mfma_f32_32x32x16_bf16 v[160:175], v[148:151], v[196:199], v[160:175]
	v_mfma_f32_32x32x16_bf16 v[160:175], v[152:155], v[200:203], v[160:175]
	v_mfma_f32_32x32x16_bf16 v[160:175], v[156:159], v[204:207], v[160:175]
	s_cbranch_scc0 .Lfz2o_c0
	v_exp_f32_e32 v144, v212
	v_exp_f32_e32 v145, v213
	v_exp_f32_e32 v146, v214
	v_exp_f32_e32 v147, v215
	v_exp_f32_e32 v148, v216
	v_exp_f32_e32 v149, v217
	v_exp_f32_e32 v150, v218
	v_exp_f32_e32 v151, v219
	v_exp_f32_e32 v152, v220
	v_exp_f32_e32 v153, v221
	v_exp_f32_e32 v154, v222
	v_exp_f32_e32 v155, v223
	v_exp_f32_e32 v156, v224
	v_exp_f32_e32 v157, v225
	v_exp_f32_e32 v158, v226
	v_exp_f32_e32 v159, v227
	v_add_f32_e32 v252, v144, v145
	v_add_f32_e32 v253, v146, v147
	v_add_f32_e32 v254, v148, v149
	v_add_f32_e32 v255, v150, v151
	v_add_f32_e32 v252, v252, v152
	v_add_f32_e32 v253, v253, v153
	v_add_f32_e32 v254, v254, v154
	v_add_f32_e32 v255, v255, v155
	v_add_f32_e32 v252, v252, v156
	v_add_f32_e32 v253, v253, v157
	v_add_f32_e32 v254, v254, v158
	v_add_f32_e32 v255, v255, v159
	v_cvt_pk_bf16_f32 v6, v144, v145
	v_cvt_pk_bf16_f32 v7, v146, v147
	v_add_f32_e32 v252, v252, v253
	v_add_f32_e32 v254, v254, v255
	v_cvt_pk_bf16_f32 v8, v148, v149
	v_cvt_pk_bf16_f32 v9, v150, v151
	v_cvt_pk_bf16_f32 v208, v152, v153
	v_add_f32_e32 v252, v252, v254
	v_cvt_pk_bf16_f32 v209, v154, v155
	v_cvt_pk_bf16_f32 v210, v156, v157
	v_cvt_pk_bf16_f32 v211, v158, v159
	v_add_u32_e32 v253, 0xde801b54, v252
	v_cmp_gt_u32_e32 vcc, 0x3bff7543, v253
	s_cmp_lg_u64 vcc, exec
	s_cbranch_scc1 .LBB0_444
	v_add_f32_e32 v15, v15, v252
	v_exp_f32_e32 v144, v160
	v_exp_f32_e32 v145, v161
	v_exp_f32_e32 v146, v162
	v_exp_f32_e32 v147, v163
	v_exp_f32_e32 v148, v164
	v_exp_f32_e32 v149, v165
	v_exp_f32_e32 v150, v166
	v_exp_f32_e32 v151, v167
	v_exp_f32_e32 v152, v168
	v_exp_f32_e32 v153, v169
	v_exp_f32_e32 v154, v170
	v_exp_f32_e32 v155, v171
	v_exp_f32_e32 v156, v172
	v_exp_f32_e32 v157, v173
	v_exp_f32_e32 v158, v174
	v_exp_f32_e32 v159, v175
	v_add_f32_e32 v252, v144, v145
	v_add_f32_e32 v253, v146, v147
	v_add_f32_e32 v254, v148, v149
	v_add_f32_e32 v255, v150, v151
	v_add_f32_e32 v252, v252, v152
	v_add_f32_e32 v253, v253, v153
	v_add_f32_e32 v254, v254, v154
	v_add_f32_e32 v255, v255, v155
	v_add_f32_e32 v252, v252, v156
	v_add_f32_e32 v253, v253, v157
	v_add_f32_e32 v254, v254, v158
	v_add_f32_e32 v255, v255, v159
	v_cvt_pk_bf16_f32 v2, v144, v145
	v_cvt_pk_bf16_f32 v3, v146, v147
	v_add_f32_e32 v252, v252, v253
	v_add_f32_e32 v254, v254, v255
	v_cvt_pk_bf16_f32 v4, v148, v149
	v_cvt_pk_bf16_f32 v5, v150, v151
	v_cvt_pk_bf16_f32 v10, v152, v153
	v_add_f32_e32 v252, v252, v254
	v_cvt_pk_bf16_f32 v11, v154, v155
	v_cvt_pk_bf16_f32 v12, v156, v157
	v_cvt_pk_bf16_f32 v13, v158, v159
	v_add_u32_e32 v253, 0xde801b54, v252
	v_cmp_gt_u32_e32 vcc, 0x3bff7543, v253
	s_cmp_lg_u64 vcc, exec
	s_cbranch_scc1 .Lfzsb2_c0
	v_add_f32_e32 v14, v14, v252
.LBB0_429:
	ds_read_b64_tr_b16 v[160:161], v242 offset:0x2000
	ds_read_b64_tr_b16 v[162:163], v242 offset:0x2100
	ds_read_b64_tr_b16 v[164:165], v242 offset:0x3000
	ds_read_b64_tr_b16 v[166:167], v242 offset:0x3100
	s_waitcnt lgkmcnt(2)
	v_mfma_f32_32x32x16_bf16 v[128:143], v[6:9], v[160:163], v[128:143]
	ds_read_b64_tr_b16 v[168:169], v242 offset:0x2200
	s_nop 0
	v_mfma_f32_32x32x16_bf16 v[96:111], v[2:5], v[160:163], v[96:111]
	ds_read_b64_tr_b16 v[170:171], v242 offset:0x2300
	s_waitcnt lgkmcnt(2)
	v_mfma_f32_32x32x16_bf16 v[128:143], v[208:211], v[164:167], v[128:143]
	ds_read_b64_tr_b16 v[172:173], v242 offset:0x3200
	s_nop 0
	v_mfma_f32_32x32x16_bf16 v[96:111], v[10:13], v[164:167], v[96:111]
	ds_read_b64_tr_b16 v[174:175], v242 offset:0x3300
	s_waitcnt lgkmcnt(2)
	v_mfma_f32_32x32x16_bf16 v[112:127], v[6:9], v[168:171], v[112:127]
	ds_read_b64_tr_b16 v[160:161], v242 offset:0x2400
	s_nop 0
	v_mfma_f32_32x32x16_bf16 v[80:95], v[2:5], v[168:171], v[80:95]
	ds_read_b64_tr_b16 v[162:163], v242 offset:0x2500
	s_waitcnt lgkmcnt(2)
	v_mfma_f32_32x32x16_bf16 v[112:127], v[208:211], v[172:175], v[112:127]
	ds_read_b64_tr_b16 v[164:165], v242 offset:0x3400
	s_nop 0
	v_mfma_f32_32x32x16_bf16 v[80:95], v[10:13], v[172:175], v[80:95]
	ds_read_b64_tr_b16 v[166:167], v242 offset:0x3500
	s_waitcnt lgkmcnt(2)
	v_mfma_f32_32x32x16_bf16 v[64:79], v[6:9], v[160:163], v[64:79]
	ds_read_b64_tr_b16 v[168:169], v242 offset:0x2600
	s_nop 0
	v_mfma_f32_32x32x16_bf16 v[32:47], v[2:5], v[160:163], v[32:47]
	ds_read_b64_tr_b16 v[170:171], v242 offset:0x2700
	s_waitcnt lgkmcnt(2)
	v_mfma_f32_32x32x16_bf16 v[64:79], v[208:211], v[164:167], v[64:79]
	ds_read_b64_tr_b16 v[172:173], v242 offset:0x3600
	s_nop 0
	v_mfma_f32_32x32x16_bf16 v[32:47], v[10:13], v[164:167], v[32:47]
	ds_read_b64_tr_b16 v[174:175], v242 offset:0x3700
	s_waitcnt lgkmcnt(2)
	v_mfma_f32_32x32x16_bf16 v[48:63], v[6:9], v[168:171], v[48:63]
	s_nop 0
	v_mfma_f32_32x32x16_bf16 v[16:31], v[2:5], v[168:171], v[16:31]
	s_waitcnt lgkmcnt(0)
	v_mfma_f32_32x32x16_bf16 v[48:63], v[208:211], v[172:175], v[48:63]
	s_nop 0
	v_mfma_f32_32x32x16_bf16 v[16:31], v[10:13], v[172:175], v[16:31]
	s_branch .LBB0_388

.LBB0_1267:
	v_add_u32_e32 v242, s27, v234
	ds_read_b64_tr_b16 v[160:161], v242 offset:0x0
	ds_read_b64_tr_b16 v[162:163], v242 offset:0x100
	ds_read_b64_tr_b16 v[164:165], v242 offset:0x1000
	ds_read_b64_tr_b16 v[166:167], v242 offset:0x1100
	s_waitcnt lgkmcnt(2)
	v_mfma_f32_32x32x16_bf16 v[128:143], v[216:219], v[160:163], v[128:143]
	ds_read_b64_tr_b16 v[168:169], v242 offset:0x200
	s_nop 0
	v_mfma_f32_32x32x16_bf16 v[96:111], v[212:215], v[160:163], v[96:111]
	ds_read_b64_tr_b16 v[170:171], v242 offset:0x300
	s_waitcnt lgkmcnt(2)
	v_mfma_f32_32x32x16_bf16 v[128:143], v[224:227], v[164:167], v[128:143]
	ds_read_b64_tr_b16 v[172:173], v242 offset:0x1200
	s_nop 0
	v_mfma_f32_32x32x16_bf16 v[96:111], v[220:223], v[164:167], v[96:111]
	ds_read_b64_tr_b16 v[174:175], v242 offset:0x1300
	s_waitcnt lgkmcnt(2)
	v_mfma_f32_32x32x16_bf16 v[112:127], v[216:219], v[168:171], v[112:127]
	ds_read_b64_tr_b16 v[160:161], v242 offset:0x400
	s_nop 0
	v_mfma_f32_32x32x16_bf16 v[80:95], v[212:215], v[168:171], v[80:95]
	ds_read_b64_tr_b16 v[162:163], v242 offset:0x500
	s_waitcnt lgkmcnt(2)
	v_mfma_f32_32x32x16_bf16 v[112:127], v[224:227], v[172:175], v[112:127]
	ds_read_b64_tr_b16 v[164:165], v242 offset:0x1400
	s_nop 0
	v_mfma_f32_32x32x16_bf16 v[80:95], v[220:223], v[172:175], v[80:95]
	ds_read_b64_tr_b16 v[166:167], v242 offset:0x1500
	ds_read_b128 v[144:147], v241 offset:0x2000
	ds_read_b128 v[148:151], v240 offset:0x2000
	ds_read_b128 v[152:155], v239 offset:0x2000
	ds_read_b128 v[156:159], v0 offset:0x2000
	s_waitcnt lgkmcnt(6)
	v_mfma_f32_32x32x16_bf16 v[64:79], v[216:219], v[160:163], v[64:79]
	ds_read_b64_tr_b16 v[168:169], v242 offset:0x600
	s_nop 0
	v_mfma_f32_32x32x16_bf16 v[48:63], v[212:215], v[160:163], v[48:63]
	ds_read_b64_tr_b16 v[170:171], v242 offset:0x700
	s_waitcnt lgkmcnt(6)
	v_mfma_f32_32x32x16_bf16 v[64:79], v[224:227], v[164:167], v[64:79]
	ds_read_b64_tr_b16 v[172:173], v242 offset:0x1600
	s_nop 0
	v_mfma_f32_32x32x16_bf16 v[48:63], v[220:223], v[164:167], v[48:63]
	ds_read_b64_tr_b16 v[174:175], v242 offset:0x1700
	s_waitcnt lgkmcnt(2)
	v_mfma_f32_32x32x16_bf16 v[32:47], v[216:219], v[168:171], v[32:47]
	s_nop 0
	v_mfma_f32_32x32x16_bf16 v[16:31], v[212:215], v[168:171], v[16:31]
	s_waitcnt lgkmcnt(0)
	v_mfma_f32_32x32x16_bf16 v[32:47], v[224:227], v[172:175], v[32:47]
	s_nop 0
	v_mfma_f32_32x32x16_bf16 v[16:31], v[220:223], v[172:175], v[16:31]
	s_waitcnt lgkmcnt(0)
	v_mfma_f32_32x32x16_bf16 v[212:227], v[144:147], v[176:179], 0
	v_mfma_f32_32x32x16_bf16 v[212:227], v[148:151], v[180:183], v[212:227]
	v_mfma_f32_32x32x16_bf16 v[212:227], v[152:155], v[184:187], v[212:227]
	v_mfma_f32_32x32x16_bf16 v[212:227], v[156:159], v[188:191], v[212:227]
	ds_read_b128 v[144:147], v241 offset:0x2080
	ds_read_b128 v[148:151], v240 offset:0x2080
	ds_read_b128 v[152:155], v239 offset:0x2080
	ds_read_b128 v[156:159], v0 offset:0x2080
	v_cmp_eq_f32_e32 vcc, 0, v238
	v_cmp_eq_f32_e64 s[10:11], 0, v237
	s_and_b64 s[0:1], vcc, s[10:11]
	s_cmp_eq_u64 s[0:1], exec
	s_waitcnt lgkmcnt(0)
	v_mfma_f32_32x32x16_bf16 v[160:175], v[144:147], v[192:195], 0
	v_mfma_f32_32x32x16_bf16 v[160:175], v[148:151], v[196:199], v[160:175]
	v_mfma_f32_32x32x16_bf16 v[160:175], v[152:155], v[200:203], v[160:175]
	v_mfma_f32_32x32x16_bf16 v[160:175], v[156:159], v[204:207], v[160:175]
	s_cbranch_scc0 .Lfz2o_c1
	v_exp_f32_e32 v144, v212
	v_exp_f32_e32 v145, v213
	v_exp_f32_e32 v146, v214
	v_exp_f32_e32 v147, v215
	v_exp_f32_e32 v148, v216
	v_exp_f32_e32 v149, v217
	v_exp_f32_e32 v150, v218
	v_exp_f32_e32 v151, v219
	v_exp_f32_e32 v152, v220
	v_exp_f32_e32 v153, v221
	v_exp_f32_e32 v154, v222
	v_exp_f32_e32 v155, v223
	v_exp_f32_e32 v156, v224
	v_exp_f32_e32 v157, v225
	v_exp_f32_e32 v158, v226
	v_exp_f32_e32 v159, v227
	v_add_f32_e32 v252, v144, v145
	v_add_f32_e32 v253, v146, v147
	v_add_f32_e32 v254, v148, v149
	v_add_f32_e32 v255, v150, v151
	v_add_f32_e32 v252, v252, v152
	v_add_f32_e32 v253, v253, v153
	v_add_f32_e32 v254, v254, v154
	v_add_f32_e32 v255, v255, v155
	v_add_f32_e32 v252, v252, v156
	v_add_f32_e32 v253, v253, v157
	v_add_f32_e32 v254, v254, v158
	v_add_f32_e32 v255, v255, v159
	v_cvt_pk_bf16_f32 v6, v144, v145
	v_cvt_pk_bf16_f32 v7, v146, v147
	v_add_f32_e32 v252, v252, v253
	v_add_f32_e32 v254, v254, v255
	v_cvt_pk_bf16_f32 v8, v148, v149
	v_cvt_pk_bf16_f32 v9, v150, v151
	v_cvt_pk_bf16_f32 v208, v152, v153
	v_add_f32_e32 v252, v252, v254
	v_cvt_pk_bf16_f32 v209, v154, v155
	v_cvt_pk_bf16_f32 v210, v156, v157
	v_cvt_pk_bf16_f32 v211, v158, v159
	v_add_u32_e32 v253, 0xde801b54, v252
	v_cmp_gt_u32_e32 vcc, 0x3bff7543, v253
	s_cmp_lg_u64 vcc, exec
	s_cbranch_scc1 .LBB0_1298
	v_add_f32_e32 v15, v15, v252
	v_exp_f32_e32 v144, v160
	v_exp_f32_e32 v145, v161
	v_exp_f32_e32 v146, v162
	v_exp_f32_e32 v147, v163
	v_exp_f32_e32 v148, v164
	v_exp_f32_e32 v149, v165
	v_exp_f32_e32 v150, v166
	v_exp_f32_e32 v151, v167
	v_exp_f32_e32 v152, v168
	v_exp_f32_e32 v153, v169
	v_exp_f32_e32 v154, v170
	v_exp_f32_e32 v155, v171
	v_exp_f32_e32 v156, v172
	v_exp_f32_e32 v157, v173
	v_exp_f32_e32 v158, v174
	v_exp_f32_e32 v159, v175
	v_add_f32_e32 v252, v144, v145
	v_add_f32_e32 v253, v146, v147
	v_add_f32_e32 v254, v148, v149
	v_add_f32_e32 v255, v150, v151
	v_add_f32_e32 v252, v252, v152
	v_add_f32_e32 v253, v253, v153
	v_add_f32_e32 v254, v254, v154
	v_add_f32_e32 v255, v255, v155
	v_add_f32_e32 v252, v252, v156
	v_add_f32_e32 v253, v253, v157
	v_add_f32_e32 v254, v254, v158
	v_add_f32_e32 v255, v255, v159
	v_cvt_pk_bf16_f32 v2, v144, v145
	v_cvt_pk_bf16_f32 v3, v146, v147
	v_add_f32_e32 v252, v252, v253
	v_add_f32_e32 v254, v254, v255
	v_cvt_pk_bf16_f32 v4, v148, v149
	v_cvt_pk_bf16_f32 v5, v150, v151
	v_cvt_pk_bf16_f32 v10, v152, v153
	v_add_f32_e32 v252, v252, v254
	v_cvt_pk_bf16_f32 v11, v154, v155
	v_cvt_pk_bf16_f32 v12, v156, v157
	v_cvt_pk_bf16_f32 v13, v158, v159
	v_add_u32_e32 v253, 0xde801b54, v252
	v_cmp_gt_u32_e32 vcc, 0x3bff7543, v253
	s_cmp_lg_u64 vcc, exec
	s_cbranch_scc1 .Lfzsb2_c1
	v_add_f32_e32 v14, v14, v252
.LBB0_1283:
	ds_read_b64_tr_b16 v[160:161], v242 offset:0x2000
	ds_read_b64_tr_b16 v[162:163], v242 offset:0x2100
	ds_read_b64_tr_b16 v[164:165], v242 offset:0x3000
	ds_read_b64_tr_b16 v[166:167], v242 offset:0x3100
	s_waitcnt lgkmcnt(2)
	v_mfma_f32_32x32x16_bf16 v[128:143], v[6:9], v[160:163], v[128:143]
	ds_read_b64_tr_b16 v[168:169], v242 offset:0x2200
	s_nop 0
	v_mfma_f32_32x32x16_bf16 v[96:111], v[2:5], v[160:163], v[96:111]
	ds_read_b64_tr_b16 v[170:171], v242 offset:0x2300
	s_waitcnt lgkmcnt(2)
	v_mfma_f32_32x32x16_bf16 v[128:143], v[208:211], v[164:167], v[128:143]
	ds_read_b64_tr_b16 v[172:173], v242 offset:0x3200
	s_nop 0
	v_mfma_f32_32x32x16_bf16 v[96:111], v[10:13], v[164:167], v[96:111]
	ds_read_b64_tr_b16 v[174:175], v242 offset:0x3300
	s_waitcnt lgkmcnt(2)
	v_mfma_f32_32x32x16_bf16 v[112:127], v[6:9], v[168:171], v[112:127]
	ds_read_b64_tr_b16 v[160:161], v242 offset:0x2400
	s_nop 0
	v_mfma_f32_32x32x16_bf16 v[80:95], v[2:5], v[168:171], v[80:95]
	ds_read_b64_tr_b16 v[162:163], v242 offset:0x2500
	s_waitcnt lgkmcnt(2)
	v_mfma_f32_32x32x16_bf16 v[112:127], v[208:211], v[172:175], v[112:127]
	ds_read_b64_tr_b16 v[164:165], v242 offset:0x3400
	s_nop 0
	v_mfma_f32_32x32x16_bf16 v[80:95], v[10:13], v[172:175], v[80:95]
	ds_read_b64_tr_b16 v[166:167], v242 offset:0x3500
	s_waitcnt lgkmcnt(2)
	v_mfma_f32_32x32x16_bf16 v[64:79], v[6:9], v[160:163], v[64:79]
	ds_read_b64_tr_b16 v[168:169], v242 offset:0x2600
	s_nop 0
	v_mfma_f32_32x32x16_bf16 v[48:63], v[2:5], v[160:163], v[48:63]
	ds_read_b64_tr_b16 v[170:171], v242 offset:0x2700
	s_waitcnt lgkmcnt(2)
	v_mfma_f32_32x32x16_bf16 v[64:79], v[208:211], v[164:167], v[64:79]
	ds_read_b64_tr_b16 v[172:173], v242 offset:0x3600
	s_nop 0
	v_mfma_f32_32x32x16_bf16 v[48:63], v[10:13], v[164:167], v[48:63]
	ds_read_b64_tr_b16 v[174:175], v242 offset:0x3700
	s_waitcnt lgkmcnt(2)
	v_mfma_f32_32x32x16_bf16 v[32:47], v[6:9], v[168:171], v[32:47]
	s_nop 0
	v_mfma_f32_32x32x16_bf16 v[16:31], v[2:5], v[168:171], v[16:31]
	s_waitcnt lgkmcnt(0)
	v_mfma_f32_32x32x16_bf16 v[32:47], v[208:211], v[172:175], v[32:47]
	s_nop 0
	v_mfma_f32_32x32x16_bf16 v[16:31], v[10:13], v[172:175], v[16:31]
	s_branch .LBB0_1242

.LBB0_2121:
	v_add_u32_e32 v242, s27, v234
	ds_read_b64_tr_b16 v[160:161], v242 offset:0x0
	ds_read_b64_tr_b16 v[162:163], v242 offset:0x100
	ds_read_b64_tr_b16 v[164:165], v242 offset:0x1000
	ds_read_b64_tr_b16 v[166:167], v242 offset:0x1100
	s_waitcnt lgkmcnt(2)
	v_mfma_f32_32x32x16_bf16 v[128:143], v[216:219], v[160:163], v[128:143]
	ds_read_b64_tr_b16 v[168:169], v242 offset:0x200
	s_nop 0
	v_mfma_f32_32x32x16_bf16 v[96:111], v[212:215], v[160:163], v[96:111]
	ds_read_b64_tr_b16 v[170:171], v242 offset:0x300
	s_waitcnt lgkmcnt(2)
	v_mfma_f32_32x32x16_bf16 v[128:143], v[224:227], v[164:167], v[128:143]
	ds_read_b64_tr_b16 v[172:173], v242 offset:0x1200
	s_nop 0
	v_mfma_f32_32x32x16_bf16 v[96:111], v[220:223], v[164:167], v[96:111]
	ds_read_b64_tr_b16 v[174:175], v242 offset:0x1300
	s_waitcnt lgkmcnt(2)
	v_mfma_f32_32x32x16_bf16 v[112:127], v[216:219], v[168:171], v[112:127]
	ds_read_b64_tr_b16 v[160:161], v242 offset:0x400
	s_nop 0
	v_mfma_f32_32x32x16_bf16 v[80:95], v[212:215], v[168:171], v[80:95]
	ds_read_b64_tr_b16 v[162:163], v242 offset:0x500
	s_waitcnt lgkmcnt(2)
	v_mfma_f32_32x32x16_bf16 v[112:127], v[224:227], v[172:175], v[112:127]
	ds_read_b64_tr_b16 v[164:165], v242 offset:0x1400
	s_nop 0
	v_mfma_f32_32x32x16_bf16 v[80:95], v[220:223], v[172:175], v[80:95]
	ds_read_b64_tr_b16 v[166:167], v242 offset:0x1500
	ds_read_b128 v[144:147], v241 offset:0x2000
	ds_read_b128 v[148:151], v240 offset:0x2000
	ds_read_b128 v[156:159], v239 offset:0x2000
	ds_read_b128 v[244:247], v0 offset:0x2000
	s_waitcnt lgkmcnt(6)
	v_mfma_f32_32x32x16_bf16 v[64:79], v[216:219], v[160:163], v[64:79]
	ds_read_b64_tr_b16 v[168:169], v242 offset:0x600
	s_nop 0
	v_mfma_f32_32x32x16_bf16 v[32:47], v[212:215], v[160:163], v[32:47]
	ds_read_b64_tr_b16 v[170:171], v242 offset:0x700
	s_waitcnt lgkmcnt(6)
	v_mfma_f32_32x32x16_bf16 v[64:79], v[224:227], v[164:167], v[64:79]
	ds_read_b64_tr_b16 v[172:173], v242 offset:0x1600
	s_nop 0
	v_mfma_f32_32x32x16_bf16 v[32:47], v[220:223], v[164:167], v[32:47]
	ds_read_b64_tr_b16 v[174:175], v242 offset:0x1700
	s_waitcnt lgkmcnt(2)
	v_mfma_f32_32x32x16_bf16 v[48:63], v[216:219], v[168:171], v[48:63]
	s_nop 0
	v_mfma_f32_32x32x16_bf16 v[16:31], v[212:215], v[168:171], v[16:31]
	s_waitcnt lgkmcnt(0)
	v_mfma_f32_32x32x16_bf16 v[48:63], v[224:227], v[172:175], v[48:63]
	s_nop 0
	v_mfma_f32_32x32x16_bf16 v[16:31], v[220:223], v[172:175], v[16:31]
	s_waitcnt lgkmcnt(0)
	v_mfma_f32_32x32x16_bf16 v[212:227], v[144:147], v[176:179], 0
	v_mfma_f32_32x32x16_bf16 v[212:227], v[148:151], v[180:183], v[212:227]
	v_mfma_f32_32x32x16_bf16 v[212:227], v[156:159], v[184:187], v[212:227]
	v_mfma_f32_32x32x16_bf16 v[212:227], v[244:247], v[188:191], v[212:227]
	ds_read_b128 v[144:147], v241 offset:0x2080
	ds_read_b128 v[148:151], v240 offset:0x2080
	ds_read_b128 v[152:155], v239 offset:0x2080
	ds_read_b128 v[156:159], v0 offset:0x2080
	v_cmp_eq_f32_e32 vcc, 0, v238
	v_cmp_eq_f32_e64 s[6:7], 0, v237
	s_and_b64 s[0:1], vcc, s[6:7]
	s_cmp_eq_u64 s[0:1], exec
	s_waitcnt lgkmcnt(0)
	v_mfma_f32_32x32x16_bf16 v[160:175], v[144:147], v[192:195], 0
	v_mfma_f32_32x32x16_bf16 v[160:175], v[148:151], v[196:199], v[160:175]
	v_mfma_f32_32x32x16_bf16 v[160:175], v[152:155], v[200:203], v[160:175]
	v_mfma_f32_32x32x16_bf16 v[160:175], v[156:159], v[204:207], v[160:175]
	s_cbranch_scc0 .Lfz2o_c2
	v_exp_f32_e32 v144, v212
	v_exp_f32_e32 v145, v213
	v_exp_f32_e32 v146, v214
	v_exp_f32_e32 v147, v215
	v_exp_f32_e32 v148, v216
	v_exp_f32_e32 v149, v217
	v_exp_f32_e32 v150, v218
	v_exp_f32_e32 v151, v219
	v_exp_f32_e32 v152, v220
	v_exp_f32_e32 v153, v221
	v_exp_f32_e32 v154, v222
	v_exp_f32_e32 v155, v223
	v_exp_f32_e32 v156, v224
	v_exp_f32_e32 v157, v225
	v_exp_f32_e32 v158, v226
	v_exp_f32_e32 v159, v227
	v_add_f32_e32 v252, v144, v145
	v_add_f32_e32 v253, v146, v147
	v_add_f32_e32 v254, v148, v149
	v_add_f32_e32 v255, v150, v151
	v_add_f32_e32 v252, v252, v152
	v_add_f32_e32 v253, v253, v153
	v_add_f32_e32 v254, v254, v154
	v_add_f32_e32 v255, v255, v155
	v_add_f32_e32 v252, v252, v156
	v_add_f32_e32 v253, v253, v157
	v_add_f32_e32 v254, v254, v158
	v_add_f32_e32 v255, v255, v159
	v_cvt_pk_bf16_f32 v6, v144, v145
	v_cvt_pk_bf16_f32 v7, v146, v147
	v_add_f32_e32 v252, v252, v253
	v_add_f32_e32 v254, v254, v255
	v_cvt_pk_bf16_f32 v8, v148, v149
	v_cvt_pk_bf16_f32 v9, v150, v151
	v_cvt_pk_bf16_f32 v208, v152, v153
	v_add_f32_e32 v252, v252, v254
	v_cvt_pk_bf16_f32 v209, v154, v155
	v_cvt_pk_bf16_f32 v210, v156, v157
	v_cvt_pk_bf16_f32 v211, v158, v159
	v_add_u32_e32 v253, 0xde801b54, v252
	v_cmp_gt_u32_e32 vcc, 0x3bff7543, v253
	s_cmp_lg_u64 vcc, exec
	s_cbranch_scc1 .LBB0_2152
	v_add_f32_e32 v15, v15, v252
	v_exp_f32_e32 v144, v160
	v_exp_f32_e32 v145, v161
	v_exp_f32_e32 v146, v162
	v_exp_f32_e32 v147, v163
	v_exp_f32_e32 v148, v164
	v_exp_f32_e32 v149, v165
	v_exp_f32_e32 v150, v166
	v_exp_f32_e32 v151, v167
	v_exp_f32_e32 v152, v168
	v_exp_f32_e32 v153, v169
	v_exp_f32_e32 v154, v170
	v_exp_f32_e32 v155, v171
	v_exp_f32_e32 v156, v172
	v_exp_f32_e32 v157, v173
	v_exp_f32_e32 v158, v174
	v_exp_f32_e32 v159, v175
	v_add_f32_e32 v252, v144, v145
	v_add_f32_e32 v253, v146, v147
	v_add_f32_e32 v254, v148, v149
	v_add_f32_e32 v255, v150, v151
	v_add_f32_e32 v252, v252, v152
	v_add_f32_e32 v253, v253, v153
	v_add_f32_e32 v254, v254, v154
	v_add_f32_e32 v255, v255, v155
	v_add_f32_e32 v252, v252, v156
	v_add_f32_e32 v253, v253, v157
	v_add_f32_e32 v254, v254, v158
	v_add_f32_e32 v255, v255, v159
	v_cvt_pk_bf16_f32 v2, v144, v145
	v_cvt_pk_bf16_f32 v3, v146, v147
	v_add_f32_e32 v252, v252, v253
	v_add_f32_e32 v254, v254, v255
	v_cvt_pk_bf16_f32 v4, v148, v149
	v_cvt_pk_bf16_f32 v5, v150, v151
	v_cvt_pk_bf16_f32 v10, v152, v153
	v_add_f32_e32 v252, v252, v254
	v_cvt_pk_bf16_f32 v11, v154, v155
	v_cvt_pk_bf16_f32 v12, v156, v157
	v_cvt_pk_bf16_f32 v13, v158, v159
	v_add_u32_e32 v253, 0xde801b54, v252
	v_cmp_gt_u32_e32 vcc, 0x3bff7543, v253
	s_cmp_lg_u64 vcc, exec
	s_cbranch_scc1 .Lfzsb2_c2
	v_add_f32_e32 v14, v14, v252
